# qk-prep rows: 8-lane sum of squares via DPP (quad_perm x2 + row_half_mirror) instead of 3 serialized ds_bpermute round trips
# speedup vs baseline: 1.0023x; 1.0023x over previous
.LBB0_341:
	v_cmp_gt_u32_e64 s[44:45], 64, v11
	s_and_b64 s[24:25], s[96:97], s[44:45]
	v_cmp_lt_u32_e64 s[42:43], 63, v11
	s_xor_b64 s[34:35], s[24:25], -1
	s_and_saveexec_b64 s[24:25], s[34:35]
	s_cbranch_execz .LBB0_340
	v_and_b32_e32 v24, 63, v11
	s_andn2_b64 vcc, exec, s[26:27]
	s_mov_b64 s[34:35], -1
	s_cbranch_vccnz .LBB0_346
	v_cndmask_b32_e64 v6, v54, v52, s[44:45]
	v_cndmask_b32_e64 v7, v55, v53, s[44:45]
	v_readlane_b32 s34, v252, 36
	v_readlane_b32 s35, v252, 37
	v_or_b32_e32 v25, s75, v24
	v_and_b32_e32 v4, 0xfffffe00, v32
	v_mov_b64_e32 v[2:3], s[34:35]
	s_movk_i32 s34, 0xc00
	v_mad_u64_u32 v[2:3], s[34:35], v25, s34, v[2:3]
	v_ashrrev_i32_e32 v5, 31, v4
	v_lshl_add_u64 v[2:3], v[4:5], 1, v[2:3]
	v_lshlrev_b32_e32 v8, 1, v10
	v_mov_b32_e32 v9, v1
	v_lshl_add_u64 v[2:3], v[2:3], 0, v[0:1]
	v_lshl_add_u64 v[2:3], v[2:3], 0, v[8:9]
	global_load_dwordx4 v[2:5], v[2:3], off
	v_lshlrev_b32_e32 v8, 2, v10
	v_lshlrev_b32_e32 v25, 7, v25
	v_mov_b32_e32 v31, v1
	v_and_b32_e32 v30, 0x7ff80, v25
	v_lshl_add_u64 v[38:39], v[12:13], 0, v[30:31]
	v_lshl_add_u64 v[30:31], v[14:15], 0, v[30:31]
	v_cmp_lt_i32_e32 vcc, v227, v221
	s_nop 0
	v_lshl_add_u64 v[6:7], s[40:41], 2, v[6:7]
	v_lshl_add_u64 v[26:27], v[6:7], 0, v[8:9]
	global_load_dwordx4 v[6:9], v[26:27], off offset:16
	s_nop 0
	global_load_dwordx4 v[26:29], v[26:27], off
	s_nop 0
	global_load_dwordx4 v[34:37], v[30:31], off
	s_nop 0
	global_load_dwordx4 v[38:41], v[38:39], off
	s_waitcnt vmcnt(4)
	v_cndmask_b32_e32 v25, v220, v227, vcc
	v_lshlrev_b32_e32 v25, 2, v25
	v_cmp_lt_i32_e32 vcc, v226, v221
	v_lshlrev_b32_e32 v30, 16, v2
	v_and_b32_e32 v31, 0xffff0000, v2
	v_lshlrev_b32_e32 v2, 16, v3
	v_and_b32_e32 v3, 0xffff0000, v3
	v_pk_mul_f32 v[46:47], v[30:31], v[30:31]
	v_pk_mul_f32 v[48:49], v[2:3], v[2:3]
	v_add_f32_e32 v33, v46, v47
	v_lshlrev_b32_e32 v42, 16, v4
	v_and_b32_e32 v43, 0xffff0000, v4
	v_add_f32_e32 v33, v33, v48
	v_pk_mul_f32 v[50:51], v[42:43], v[42:43]
	v_add_f32_e32 v33, v49, v33
	v_lshlrev_b32_e32 v4, 16, v5
	v_and_b32_e32 v5, 0xffff0000, v5
	v_add_f32_e32 v33, v50, v33
	v_pk_mul_f32 v[44:45], v[4:5], v[4:5]
	v_add_f32_e32 v33, v51, v33
	v_add_f32_e32 v33, v44, v33
	v_add_f32_e32 v33, v45, v33
	s_nop 1
	v_add_f32_dpp v25, v33, v33 quad_perm:[1,0,3,2] row_mask:0xf bank_mask:0xf
	s_nop 1
	v_add_f32_dpp v25, v25, v25 quad_perm:[2,3,0,1] row_mask:0xf bank_mask:0xf
	s_nop 1
	v_add_f32_dpp v25, v25, v25 row_half_mirror row_mask:0xf bank_mask:0xf
	v_fmamk_f32 v25, v25, 0x3c800000, v187
	v_mul_f32_e32 v33, 0x4b800000, v25
	v_cmp_gt_f32_e32 vcc, s82, v25
	s_nop 1
	v_cndmask_b32_e32 v25, v25, v33, vcc
	v_rsq_f32_e32 v25, v25
	s_nop 0
	v_mul_f32_e32 v33, 0x45800000, v25
	v_cndmask_b32_e32 v44, v25, v33, vcc
	v_pk_mul_f32 v[30:31], v[44:45], v[30:31] op_sel_hi:[0,1]
	v_pk_mul_f32 v[2:3], v[44:45], v[2:3] op_sel_hi:[0,1]
	v_pk_mul_f32 v[42:43], v[44:45], v[42:43] op_sel_hi:[0,1]
	v_pk_mul_f32 v[4:5], v[44:45], v[4:5] op_sel_hi:[0,1]
	s_waitcnt vmcnt(2)
	v_pk_mul_f32 v[26:27], v[26:27], v[30:31]
	v_pk_mul_f32 v[28:29], v[28:29], v[2:3]
	v_pk_mul_f32 v[30:31], v[6:7], v[42:43]
	v_pk_mul_f32 v[42:43], v[8:9], v[4:5]
	s_waitcnt vmcnt(1)
	v_pk_mul_f32 v[44:45], v[34:35], v[26:27] op_sel:[0,1] op_sel_hi:[0,0]
	v_pk_mul_f32 v[6:7], v[34:35], v[28:29] op_sel:[1,1] op_sel_hi:[1,0]
	v_pk_mul_f32 v[8:9], v[30:31], v[36:37] op_sel:[1,0] op_sel_hi:[0,0]
	s_waitcnt vmcnt(0)
	v_pk_mul_f32 v[46:47], v[38:39], v[26:27] op_sel_hi:[0,1]
	v_mov_b32_e32 v36, v41
	v_mul_f32_e32 v34, v37, v43
	v_mul_f32_e32 v48, v41, v43
	v_pk_fma_f32 v[2:3], v[38:39], v[26:27], v[44:45] op_sel_hi:[0,1,1]
	v_pk_fma_f32 v[4:5], v[38:39], v[28:29], v[6:7] op_sel:[1,0,0] neg_lo:[0,0,1] neg_hi:[0,0,1]
	v_pk_fma_f32 v[26:27], v[38:39], v[28:29], v[6:7] op_sel:[1,0,0]
	v_pk_fma_f32 v[6:7], v[40:41], v[30:31], v[8:9] op_sel_hi:[0,1,1] neg_lo:[0,0,1] neg_hi:[0,0,1]
	v_pk_fma_f32 v[28:29], v[40:41], v[30:31], v[8:9] op_sel_hi:[0,1,1]
	v_mov_b32_e32 v40, v37
	v_pk_fma_f32 v[8:9], v[36:37], v[42:43], v[34:35] op_sel_hi:[1,1,0] neg_lo:[0,0,1] neg_hi:[0,0,1]
	v_pk_fma_f32 v[30:31], v[40:41], v[42:43], v[48:49] op_sel_hi:[1,1,0]
	v_sub_f32_e32 v2, v46, v44
	s_cbranch_execz .LBB0_347

.LBB0_445:
	v_cmp_gt_u32_e64 s[44:45], 64, v11
	s_and_b64 s[28:29], s[20:21], s[44:45]
	v_cmp_lt_u32_e64 s[42:43], 63, v11
	s_xor_b64 s[34:35], s[28:29], -1
	s_and_saveexec_b64 s[28:29], s[34:35]
	s_cbranch_execz .LBB0_444
	v_and_b32_e32 v22, 63, v11
	s_andn2_b64 vcc, exec, s[4:5]
	s_mov_b64 s[34:35], -1
	s_cbranch_vccnz .LBB0_450
	v_cndmask_b32_e64 v6, v54, v52, s[44:45]
	v_cndmask_b32_e64 v7, v55, v53, s[44:45]
	v_readlane_b32 s34, v252, 36
	v_readlane_b32 s35, v252, 37
	v_or_b32_e32 v5, s76, v22
	v_and_b32_e32 v4, 0xfffffe00, v24
	v_mov_b64_e32 v[2:3], s[34:35]
	s_movk_i32 s34, 0xc00
	v_mad_u64_u32 v[2:3], s[34:35], v5, s34, v[2:3]
	v_ashrrev_i32_e32 v5, 31, v4
	v_lshl_add_u64 v[2:3], v[4:5], 1, v[2:3]
	v_lshlrev_b32_e32 v8, 1, v10
	v_mov_b32_e32 v9, v1
	v_lshl_add_u64 v[2:3], v[2:3], 0, v[0:1]
	v_lshl_add_u64 v[2:3], v[2:3], 0, v[8:9]
	global_load_dwordx4 v[2:5], v[2:3], off
	v_lshlrev_b32_e32 v8, 2, v10
	v_cmp_lt_i32_e32 vcc, v227, v221
	s_nop 0
	v_lshl_add_u64 v[6:7], s[12:13], 2, v[6:7]
	v_lshl_add_u64 v[26:27], v[6:7], 0, v[8:9]
	global_load_dwordx4 v[6:9], v[26:27], off
	s_nop 0
	global_load_dwordx4 v[26:29], v[26:27], off offset:16
	s_waitcnt vmcnt(2)
	v_cndmask_b32_e32 v23, v220, v227, vcc
	v_lshlrev_b32_e32 v23, 2, v23
	v_cmp_lt_i32_e32 vcc, v226, v221
	v_lshlrev_b32_e32 v30, 16, v2
	v_and_b32_e32 v31, 0xffff0000, v2
	v_lshlrev_b32_e32 v2, 16, v3
	v_and_b32_e32 v3, 0xffff0000, v3
	v_pk_mul_f32 v[36:37], v[30:31], v[30:31]
	v_pk_mul_f32 v[38:39], v[2:3], v[2:3]
	v_add_f32_e32 v25, v36, v37
	v_lshlrev_b32_e32 v32, 16, v4
	v_and_b32_e32 v33, 0xffff0000, v4
	v_add_f32_e32 v25, v25, v38
	v_pk_mul_f32 v[40:41], v[32:33], v[32:33]
	v_add_f32_e32 v25, v39, v25
	v_lshlrev_b32_e32 v35, 16, v5
	v_and_b32_e32 v34, 0xffff0000, v5
	v_add_f32_e32 v25, v40, v25
	v_pk_mul_f32 v[4:5], v[34:35], v[34:35]
	v_add_f32_e32 v25, v41, v25
	v_add_f32_e32 v5, v5, v25
	v_add_f32_e32 v4, v4, v5
	s_nop 1
	v_add_f32_dpp v4, v4, v4 quad_perm:[1,0,3,2] row_mask:0xf bank_mask:0xf
	s_nop 1
	v_add_f32_dpp v4, v4, v4 quad_perm:[2,3,0,1] row_mask:0xf bank_mask:0xf
	s_nop 1
	v_add_f32_dpp v4, v4, v4 row_half_mirror row_mask:0xf bank_mask:0xf
	v_fmamk_f32 v4, v4, 0x3c800000, v187
	v_mul_f32_e32 v5, 0x4b800000, v4
	v_cmp_gt_f32_e32 vcc, s82, v4
	s_nop 1
	v_cndmask_b32_e32 v4, v4, v5, vcc
	v_rsq_f32_e32 v4, v4
	s_nop 0
	v_mul_f32_e32 v5, 0x45800000, v4
	v_cndmask_b32_e32 v4, v4, v5, vcc
	v_pk_mul_f32 v[30:31], v[4:5], v[30:31] op_sel_hi:[0,1]
	v_pk_mul_f32 v[36:37], v[4:5], v[2:3] op_sel_hi:[0,1]
	v_pk_mul_f32 v[32:33], v[4:5], v[32:33] op_sel_hi:[0,1]
	v_pk_mul_f32 v[34:35], v[4:5], v[34:35] op_sel_hi:[0,1]
	s_waitcnt vmcnt(1)
	v_pk_mul_f32 v[2:3], v[6:7], v[30:31]
	v_pk_mul_f32 v[4:5], v[8:9], v[36:37]
	s_waitcnt vmcnt(0)
	v_pk_mul_f32 v[6:7], v[26:27], v[32:33]
	v_pk_mul_f32 v[8:9], v[28:29], v[34:35] op_sel:[0,1] op_sel_hi:[1,0]
	s_cbranch_execz .LBB0_451
